# speedup vs baseline: 1.0237x; 1.0014x over previous
; #define STAGE_A(Poff, off, hrow) do { const unsigned _s = (off) + (unsigned)(hrow) * lda2;                                \
;     GLDS(ldsw + (Poff), offA, srdA, _s); GLDS(ldsw + (Poff) + 8192, offA, srdA, _s + lda128); } while (0)
; #define STAGE_B(Poff, off, hrow) do { const unsigned _s = (off) + (unsigned)(hrow) * ldb2;                                \
;     GLDS(ldsw + (Poff), offB, srdB, _s); GLDS(ldsw + (Poff) + 8192, offB, srdB, _s + ldb128); } while (0)
; #define LDA(dst, b, h) _Pragma("unroll") for (int m = 0; m < 4; ++m) _Pragma("unroll") for (int k = 0; k < 2; ++k) \
;     dst[m][k] = *reinterpret_cast<const bf16x8*>((const char*)SA(b, h) + aoff + (m * 2 + k) * 1024)
; #define LDB(dst, b, h) _Pragma("unroll") for (int n = 0; n < 2; ++n) _Pragma("unroll") for (int k = 0; k < 2; ++k) \
;     dst[n][k] = *reinterpret_cast<const bf16x8*>((const char*)SB(b, h) + boff + (n * 2 + k) * 1024)
; #define WAIT_V(n) asm volatile("s_waitcnt vmcnt(" #n ")" ::: "memory")
; #define WAIT_L(n) asm volatile("s_waitcnt lgkmcnt(" #n ")" ::: "memory")
; __device__ __forceinline__ void gemm_phase(const int tid_, const GemmArgs& ga, u16* shm) {
;     ...
;       for (int t = 0; t < nt; t += 2) {
;         const bool last = t + 2 >= nt;
;         const unsigned pA1 = gA + (unsigned)(t + 1) * 128u;
;         const unsigned pA2 = last ? gAn : gA + (unsigned)(t + 2) * 128u;
;         const unsigned pB2 = last ? gBn : gB + (unsigned)(t + 2) * 128u;
;         LDB(B0, 0, 0); SCHED; LDA(At, 0, 0); STAGE_A(SAO(1, 1), pA1, HALF);
;         WAIT_L(8); BAR; WAIT_L(0); MMA(0, 0, At, B0); BAR; SCHED;
;         LDB(B1, 0, 1); STAGE_B(SBO(0, 0), pB2, 0);
;         BAR; WAIT_L(0); MMA(0, 1, At, B1); BAR;
;         LDA(At, 0, 1); STAGE_A(SAO(0, 0), pA2, 0);
;         BAR; WAIT_L(0); MMA(1, 0, At, B0); BAR; SCHED;
;         STAGE_B(SBO(0, 1), pB2, HALF);
;         WAIT_V(6); BAR; MMA(1, 1, At, B1); BAR;
;         LDB(B0, 1, 0); SCHED; LDA(At, 1, 0); STAGE_A(SAO(0, 1), pA2, HALF);
;         WAIT_L(8); BAR; WAIT_L(0); MMA(0, 0, At, B0); BAR; SCHED;
;         LDB(B1, 1, 1); STAGE_B(SBO(1, 0), pB2 + 128, 0);
;         BAR; WAIT_L(0); MMA(0, 1, At, B1); BAR;
;         LDA(At, 1, 1); STAGE_A(SAO(1, 0), pA2 + 128, 0);
;         BAR; WAIT_L(0); MMA(1, 0, At, B0); BAR; SCHED;
;         STAGE_B(SBO(1, 1), pB2 + 128, HALF);
;         WAIT_V(6); BAR; MMA(1, 1, At, B1);
.LBB0_316:
	v_add_u32_e32 v96, 0x10000, v224
	s_mov_b32 s6, s78
	ds_read_b128 v[132:135], v96
	ds_read_b128 v[136:139], v96 offset:1024
	ds_read_b128 v[140:143], v96 offset:2048
	ds_read_b128 v[144:147], v96 offset:3072
	s_add_i32 s78, s78, 2
	s_lshl_b32 s6, s6, 7
	s_lshl_b32 s7, s78, 7
	s_add_i32 s10, s79, s6
	s_add_i32 s8, s7, s54
	s_add_i32 s9, s7, s1
	s_add_i32 s11, s10, s62
	s_cmp_ge_u32 s78, s67
	s_cselect_b64 s[28:29], -1, 0
	s_and_b64 s[6:7], s[28:29], exec
	s_cselect_b32 s6, s19, s8
	ds_read_b128 v[152:155], v225
	ds_read_b128 v[156:159], v225 offset:1024
	ds_read_b128 v[160:163], v225 offset:2048
	ds_read_b128 v[164:167], v225 offset:3072
	ds_read_b128 v[168:171], v225 offset:4096
	ds_read_b128 v[172:175], v225 offset:5120
	ds_read_b128 v[176:179], v225 offset:6144
	s_mov_b32 m0, s66
	ds_read_b128 v[180:183], v225 offset:7168
	buffer_load_dwordx4 v222, s[48:51], s10 offen lds
	s_mov_b32 m0, s18
	s_nop 0
	buffer_load_dwordx4 v222, s[48:51], s11 offen lds
	v_add_u32_e32 v96, 0x14000, v224
	ds_read_b128 v[184:187], v96
	ds_read_b128 v[188:191], v96 offset:1024
	ds_read_b128 v[192:195], v96 offset:2048
	ds_read_b128 v[196:199], v96 offset:3072
	s_waitcnt lgkmcnt(0)
	s_waitcnt vmcnt(8)
	s_barrier
	v_mfma_f32_16x16x32_bf16 v[128:131], v[132:135], v[152:155], v[128:131]
	v_mfma_f32_16x16x32_bf16 v[124:127], v[140:143], v[152:155], v[124:127]
	v_mfma_f32_16x16x32_bf16 v[120:123], v[132:135], v[160:163], v[120:123]
	v_mfma_f32_16x16x32_bf16 v[116:119], v[140:143], v[160:163], v[116:119]
	v_mfma_f32_16x16x32_bf16 v[112:115], v[132:135], v[168:171], v[112:115]
	v_mfma_f32_16x16x32_bf16 v[108:111], v[140:143], v[168:171], v[108:111]
	v_mfma_f32_16x16x32_bf16 v[104:107], v[132:135], v[176:179], v[104:107]
	v_mfma_f32_16x16x32_bf16 v[98:101], v[140:143], v[176:179], v[100:103]
	v_mfma_f32_16x16x32_bf16 v[128:131], v[136:139], v[156:159], v[128:131]
	v_mfma_f32_16x16x32_bf16 v[124:127], v[144:147], v[156:159], v[124:127]
	v_mfma_f32_16x16x32_bf16 v[120:123], v[136:139], v[164:167], v[120:123]
	v_mfma_f32_16x16x32_bf16 v[116:119], v[144:147], v[164:167], v[116:119]
	v_mfma_f32_16x16x32_bf16 v[112:115], v[136:139], v[172:175], v[112:115]
	v_mfma_f32_16x16x32_bf16 v[108:111], v[144:147], v[172:175], v[108:111]
	v_mfma_f32_16x16x32_bf16 v[102:105], v[136:139], v[180:183], v[104:107]
	v_mfma_f32_16x16x32_bf16 v[98:101], v[144:147], v[180:183], v[98:101]
	v_mfma_f32_16x16x32_bf16 v[92:95], v[184:187], v[152:155], v[92:95]
	v_mfma_f32_16x16x32_bf16 v[88:91], v[192:195], v[152:155], v[88:91]
	v_mfma_f32_16x16x32_bf16 v[84:87], v[184:187], v[160:163], v[84:87]
	v_mfma_f32_16x16x32_bf16 v[80:83], v[192:195], v[160:163], v[80:83]
	v_mfma_f32_16x16x32_bf16 v[76:79], v[184:187], v[168:171], v[76:79]
	v_mfma_f32_16x16x32_bf16 v[72:75], v[192:195], v[168:171], v[72:75]
	v_mfma_f32_16x16x32_bf16 v[68:71], v[184:187], v[176:179], v[68:71]
	v_mfma_f32_16x16x32_bf16 v[64:67], v[192:195], v[176:179], v[64:67]
	v_mfma_f32_16x16x32_bf16 v[92:95], v[188:191], v[156:159], v[92:95]
	v_mfma_f32_16x16x32_bf16 v[88:91], v[196:199], v[156:159], v[88:91]
	v_mfma_f32_16x16x32_bf16 v[84:87], v[188:191], v[164:167], v[84:87]
	v_mfma_f32_16x16x32_bf16 v[80:83], v[196:199], v[164:167], v[80:83]
	v_mfma_f32_16x16x32_bf16 v[76:79], v[188:191], v[172:175], v[76:79]
	v_mfma_f32_16x16x32_bf16 v[72:75], v[196:199], v[172:175], v[72:75]
	v_mfma_f32_16x16x32_bf16 v[68:71], v[188:191], v[180:183], v[68:71]
	v_mfma_f32_16x16x32_bf16 v[64:67], v[196:199], v[180:183], v[64:67]
	s_barrier
	ds_read_b128 v[152:155], v225 offset:16384
	ds_read_b128 v[156:159], v225 offset:17408
	ds_read_b128 v[160:163], v225 offset:18432
	ds_read_b128 v[164:167], v225 offset:19456
	ds_read_b128 v[168:171], v225 offset:20480
	ds_read_b128 v[172:175], v225 offset:21504
	ds_read_b128 v[176:179], v225 offset:22528
	ds_read_b128 v[180:183], v225 offset:23552
	s_mov_b32 m0, s65
	s_cselect_b32 s7, s64, s9
	buffer_load_dwordx4 v223, s[44:47], s7 offen lds
	s_mov_b32 m0, s72
	s_add_i32 s8, s7, s63
	buffer_load_dwordx4 v223, s[44:47], s8 offen lds
	s_mov_b32 m0, s55
	s_nop 0
	buffer_load_dwordx4 v222, s[48:51], s6 offen lds
	s_mov_b32 m0, s73
	s_add_i32 s9, s6, s62
	buffer_load_dwordx4 v222, s[48:51], s9 offen lds
	s_mov_b32 m0, s52
	s_add_i32 s8, s8, s63
	buffer_load_dwordx4 v223, s[44:47], s8 offen lds
	s_mov_b32 m0, s58
	s_add_i32 s8, s8, s63
	buffer_load_dwordx4 v223, s[44:47], s8 offen lds
	s_waitcnt lgkmcnt(0)
	s_waitcnt vmcnt(8)
	s_barrier
	v_mfma_f32_16x16x32_bf16 v[60:63], v[132:135], v[152:155], v[60:63]
	v_mfma_f32_16x16x32_bf16 v[56:59], v[140:143], v[152:155], v[56:59]
	v_mfma_f32_16x16x32_bf16 v[52:55], v[132:135], v[160:163], v[52:55]
	v_mfma_f32_16x16x32_bf16 v[48:51], v[140:143], v[160:163], v[48:51]
	v_mfma_f32_16x16x32_bf16 v[44:47], v[132:135], v[168:171], v[44:47]
	v_mfma_f32_16x16x32_bf16 v[40:43], v[140:143], v[168:171], v[40:43]
	v_mfma_f32_16x16x32_bf16 v[36:39], v[132:135], v[176:179], v[36:39]
	v_mfma_f32_16x16x32_bf16 v[32:35], v[140:143], v[176:179], v[32:35]
	v_mfma_f32_16x16x32_bf16 v[60:63], v[136:139], v[156:159], v[60:63]
	v_mfma_f32_16x16x32_bf16 v[56:59], v[144:147], v[156:159], v[56:59]
	v_mfma_f32_16x16x32_bf16 v[52:55], v[136:139], v[164:167], v[52:55]
	v_mfma_f32_16x16x32_bf16 v[48:51], v[144:147], v[164:167], v[48:51]
	v_mfma_f32_16x16x32_bf16 v[44:47], v[136:139], v[172:175], v[44:47]
	v_mfma_f32_16x16x32_bf16 v[40:43], v[144:147], v[172:175], v[40:43]
	v_mfma_f32_16x16x32_bf16 v[36:39], v[136:139], v[180:183], v[36:39]
	v_mfma_f32_16x16x32_bf16 v[32:35], v[144:147], v[180:183], v[32:35]
	v_mfma_f32_16x16x32_bf16 v[28:31], v[184:187], v[152:155], v[28:31]
	v_mfma_f32_16x16x32_bf16 v[24:27], v[192:195], v[152:155], v[24:27]
	v_mfma_f32_16x16x32_bf16 v[20:23], v[184:187], v[160:163], v[20:23]
	v_mfma_f32_16x16x32_bf16 v[16:19], v[192:195], v[160:163], v[16:19]
	v_mfma_f32_16x16x32_bf16 v[12:15], v[184:187], v[168:171], v[12:15]
	v_mfma_f32_16x16x32_bf16 v[8:11], v[192:195], v[168:171], v[8:11]
	v_mfma_f32_16x16x32_bf16 v[4:7], v[184:187], v[176:179], v[4:7]
	v_mfma_f32_16x16x32_bf16 v[0:3], v[192:195], v[176:179], v[0:3]
	v_mfma_f32_16x16x32_bf16 v[28:31], v[188:191], v[156:159], v[28:31]
	v_mfma_f32_16x16x32_bf16 v[24:27], v[196:199], v[156:159], v[24:27]
	v_mfma_f32_16x16x32_bf16 v[20:23], v[188:191], v[164:167], v[20:23]
	v_mfma_f32_16x16x32_bf16 v[16:19], v[196:199], v[164:167], v[16:19]
	v_mfma_f32_16x16x32_bf16 v[12:15], v[188:191], v[172:175], v[12:15]
	v_mfma_f32_16x16x32_bf16 v[8:11], v[196:199], v[172:175], v[8:11]
	v_mfma_f32_16x16x32_bf16 v[4:7], v[188:191], v[180:183], v[4:7]
	v_mfma_f32_16x16x32_bf16 v[0:3], v[196:199], v[180:183], v[0:3]
	s_barrier
; #define STAGE_A(Poff, off, hrow) do { const unsigned _s = (off) + (unsigned)(hrow) * lda2;                                \
;     GLDS(ldsw + (Poff), offA, srdA, _s); GLDS(ldsw + (Poff) + 8192, offA, srdA, _s + lda128); } while (0)
; #define STAGE_B(Poff, off, hrow) do { const unsigned _s = (off) + (unsigned)(hrow) * ldb2;                                \
;     GLDS(ldsw + (Poff), offB, srdB, _s); GLDS(ldsw + (Poff) + 8192, offB, srdB, _s + ldb128); } while (0)
; #define LDA(dst, b, h) _Pragma("unroll") for (int m = 0; m < 4; ++m) _Pragma("unroll") for (int k = 0; k < 2; ++k) \
;     dst[m][k] = *reinterpret_cast<const bf16x8*>((const char*)SA(b, h) + aoff + (m * 2 + k) * 1024)
; #define LDB(dst, b, h) _Pragma("unroll") for (int n = 0; n < 2; ++n) _Pragma("unroll") for (int k = 0; k < 2; ++k) \
;     dst[n][k] = *reinterpret_cast<const bf16x8*>((const char*)SB(b, h) + boff + (n * 2 + k) * 1024)
; #define WAIT_V(n) asm volatile("s_waitcnt vmcnt(" #n ")" ::: "memory")
; #define WAIT_L(n) asm volatile("s_waitcnt lgkmcnt(" #n ")" ::: "memory")
; #define BAR __builtin_amdgcn_s_barrier()
; #define SCHED __builtin_amdgcn_sched_barrier(0)
; __device__ __forceinline__ void gemm_phase(const int tid_, const GemmArgs& ga, u16* shm) {
;     ...
;         WAIT_L(8); BAR; WAIT_L(0); MMA(0, 0, At, B0); BAR; SCHED;
;         LDB(B1, 0, 1); STAGE_B(SBO(0, 0), pB2, 0);
;         BAR; WAIT_L(0); MMA(0, 1, At, B1); BAR;
;         LDA(At, 0, 1); STAGE_A(SAO(0, 0), pA2, 0);
;         BAR; WAIT_L(0); MMA(1, 0, At, B0); BAR; SCHED;
;         STAGE_B(SBO(0, 1), pB2, HALF);
;         WAIT_V(6); BAR; MMA(1, 1, At, B1); BAR;
;         LDB(B0, 1, 0); SCHED; LDA(At, 1, 0); STAGE_A(SAO(0, 1), pA2, HALF);
;         WAIT_L(8); BAR; WAIT_L(0); MMA(0, 0, At, B0); BAR; SCHED;
;         LDB(B1, 1, 1); STAGE_B(SBO(1, 0), pB2 + 128, 0);
;         BAR; WAIT_L(0); MMA(0, 1, At, B1); BAR;
;         LDA(At, 1, 1); STAGE_A(SAO(1, 0), pA2 + 128, 0);
;         BAR; WAIT_L(0); MMA(1, 0, At, B0); BAR; SCHED;
;         STAGE_B(SBO(1, 1), pB2 + 128, HALF);
;         WAIT_V(6); BAR; MMA(1, 1, At, B1);
	v_add_u32_e32 v96, 0x18000, v224
	ds_read_b128 v[132:135], v96
	ds_read_b128 v[136:139], v96 offset:1024
	ds_read_b128 v[140:143], v96 offset:2048
	ds_read_b128 v[144:147], v96 offset:3072
	ds_read_b128 v[152:155], v225 offset:32768
	ds_read_b128 v[156:159], v225 offset:33792
	ds_read_b128 v[160:163], v225 offset:34816
	ds_read_b128 v[164:167], v225 offset:35840
	ds_read_b128 v[168:171], v225 offset:36864
	ds_read_b128 v[172:175], v225 offset:37888
	ds_read_b128 v[176:179], v225 offset:38912
	ds_read_b128 v[180:183], v225 offset:39936
	v_add_u32_e32 v96, 0x1c000, v224
	ds_read_b128 v[184:187], v96
	ds_read_b128 v[188:191], v96 offset:1024
	ds_read_b128 v[192:195], v96 offset:2048
	ds_read_b128 v[196:199], v96 offset:3072
	s_mov_b32 m0, s59
	s_add_i32 s8, s9, s62
	buffer_load_dwordx4 v222, s[48:51], s8 offen lds
	s_mov_b32 m0, s2
	s_add_i32 s8, s8, s62
	buffer_load_dwordx4 v222, s[48:51], s8 offen lds
	s_waitcnt lgkmcnt(0)
	s_waitcnt vmcnt(8)
	s_barrier
	v_mfma_f32_16x16x32_bf16 v[128:131], v[132:135], v[152:155], v[128:131]
	v_mfma_f32_16x16x32_bf16 v[124:127], v[140:143], v[152:155], v[124:127]
	v_mfma_f32_16x16x32_bf16 v[120:123], v[132:135], v[160:163], v[120:123]
	v_mfma_f32_16x16x32_bf16 v[116:119], v[140:143], v[160:163], v[116:119]
	v_mfma_f32_16x16x32_bf16 v[112:115], v[132:135], v[168:171], v[112:115]
	v_mfma_f32_16x16x32_bf16 v[106:109], v[140:143], v[168:171], v[108:111]
	v_mfma_f32_16x16x32_bf16 v[102:105], v[132:135], v[176:179], v[102:105]
	v_mfma_f32_16x16x32_bf16 v[98:101], v[140:143], v[176:179], v[98:101]
	v_mfma_f32_16x16x32_bf16 v[128:131], v[136:139], v[156:159], v[128:131]
	v_mfma_f32_16x16x32_bf16 v[124:127], v[144:147], v[156:159], v[124:127]
	v_mfma_f32_16x16x32_bf16 v[120:123], v[136:139], v[164:167], v[120:123]
	v_mfma_f32_16x16x32_bf16 v[116:119], v[144:147], v[164:167], v[116:119]
	v_mfma_f32_16x16x32_bf16 v[112:115], v[136:139], v[172:175], v[112:115]
	v_mfma_f32_16x16x32_bf16 v[108:111], v[144:147], v[172:175], v[106:109]
	v_mfma_f32_16x16x32_bf16 v[104:107], v[136:139], v[180:183], v[102:105]
	v_mfma_f32_16x16x32_bf16 v[100:103], v[144:147], v[180:183], v[98:101]
	v_mfma_f32_16x16x32_bf16 v[92:95], v[184:187], v[152:155], v[92:95]
	v_mfma_f32_16x16x32_bf16 v[88:91], v[192:195], v[152:155], v[88:91]
	v_mfma_f32_16x16x32_bf16 v[84:87], v[184:187], v[160:163], v[84:87]
	v_mfma_f32_16x16x32_bf16 v[80:83], v[192:195], v[160:163], v[80:83]
	v_mfma_f32_16x16x32_bf16 v[76:79], v[184:187], v[168:171], v[76:79]
	v_mfma_f32_16x16x32_bf16 v[72:75], v[192:195], v[168:171], v[72:75]
	v_mfma_f32_16x16x32_bf16 v[68:71], v[184:187], v[176:179], v[68:71]
	v_mfma_f32_16x16x32_bf16 v[64:67], v[192:195], v[176:179], v[64:67]
	v_mfma_f32_16x16x32_bf16 v[92:95], v[188:191], v[156:159], v[92:95]
	v_mfma_f32_16x16x32_bf16 v[88:91], v[196:199], v[156:159], v[88:91]
	v_mfma_f32_16x16x32_bf16 v[84:87], v[188:191], v[164:167], v[84:87]
	v_mfma_f32_16x16x32_bf16 v[80:83], v[196:199], v[164:167], v[80:83]
	v_mfma_f32_16x16x32_bf16 v[76:79], v[188:191], v[172:175], v[76:79]
	v_mfma_f32_16x16x32_bf16 v[72:75], v[196:199], v[172:175], v[72:75]
	v_mfma_f32_16x16x32_bf16 v[68:71], v[188:191], v[180:183], v[68:71]
	v_mfma_f32_16x16x32_bf16 v[64:67], v[196:199], v[180:183], v[64:67]
	s_barrier
	ds_read_b128 v[152:155], v225 offset:49152
	ds_read_b128 v[156:159], v225 offset:50176
	ds_read_b128 v[160:163], v225 offset:51200
	ds_read_b128 v[164:167], v225 offset:52224
	ds_read_b128 v[168:171], v225 offset:53248
	ds_read_b128 v[172:175], v225 offset:54272
	ds_read_b128 v[176:179], v225 offset:55296
	ds_read_b128 v[180:183], v225 offset:56320
	s_mov_b32 m0, s98
	s_addk_i32 s7, 0x80
	buffer_load_dwordx4 v223, s[44:47], s7 offen lds
	s_mov_b32 m0, s99
	s_add_i32 s7, s7, s63
	buffer_load_dwordx4 v223, s[44:47], s7 offen lds
	s_mov_b32 m0, s68
	s_addk_i32 s6, 0x80
	buffer_load_dwordx4 v222, s[48:51], s6 offen lds
	s_mov_b32 m0, s69
	s_add_i32 s6, s6, s62
	buffer_load_dwordx4 v222, s[48:51], s6 offen lds
	s_mov_b32 m0, s42
	s_add_i32 s6, s7, s63
	buffer_load_dwordx4 v223, s[44:47], s6 offen lds
	s_mov_b32 m0, s43
	s_add_i32 s6, s6, s63
	buffer_load_dwordx4 v223, s[44:47], s6 offen lds
	s_waitcnt lgkmcnt(0)
	s_waitcnt vmcnt(8)
	s_barrier
	v_mfma_f32_16x16x32_bf16 v[60:63], v[132:135], v[152:155], v[60:63]
	v_mfma_f32_16x16x32_bf16 v[56:59], v[140:143], v[152:155], v[56:59]
	v_mfma_f32_16x16x32_bf16 v[52:55], v[132:135], v[160:163], v[52:55]
	v_mfma_f32_16x16x32_bf16 v[48:51], v[140:143], v[160:163], v[48:51]
	v_mfma_f32_16x16x32_bf16 v[44:47], v[132:135], v[168:171], v[44:47]
	v_mfma_f32_16x16x32_bf16 v[40:43], v[140:143], v[168:171], v[40:43]
	v_mfma_f32_16x16x32_bf16 v[36:39], v[132:135], v[176:179], v[36:39]
	v_mfma_f32_16x16x32_bf16 v[32:35], v[140:143], v[176:179], v[32:35]
	v_mfma_f32_16x16x32_bf16 v[60:63], v[136:139], v[156:159], v[60:63]
	v_mfma_f32_16x16x32_bf16 v[56:59], v[144:147], v[156:159], v[56:59]
	v_mfma_f32_16x16x32_bf16 v[52:55], v[136:139], v[164:167], v[52:55]
	v_mfma_f32_16x16x32_bf16 v[48:51], v[144:147], v[164:167], v[48:51]
	v_mfma_f32_16x16x32_bf16 v[44:47], v[136:139], v[172:175], v[44:47]
	v_mfma_f32_16x16x32_bf16 v[40:43], v[144:147], v[172:175], v[40:43]
	v_mfma_f32_16x16x32_bf16 v[36:39], v[136:139], v[180:183], v[36:39]
	v_mfma_f32_16x16x32_bf16 v[32:35], v[144:147], v[180:183], v[32:35]
	v_mfma_f32_16x16x32_bf16 v[28:31], v[184:187], v[152:155], v[28:31]
	v_mfma_f32_16x16x32_bf16 v[24:27], v[192:195], v[152:155], v[24:27]
	v_mfma_f32_16x16x32_bf16 v[20:23], v[184:187], v[160:163], v[20:23]
	v_mfma_f32_16x16x32_bf16 v[16:19], v[192:195], v[160:163], v[16:19]
	v_mfma_f32_16x16x32_bf16 v[12:15], v[184:187], v[168:171], v[12:15]
	v_mfma_f32_16x16x32_bf16 v[8:11], v[192:195], v[168:171], v[8:11]
	v_mfma_f32_16x16x32_bf16 v[4:7], v[184:187], v[176:179], v[4:7]
	v_mfma_f32_16x16x32_bf16 v[0:3], v[192:195], v[176:179], v[0:3]
	v_mfma_f32_16x16x32_bf16 v[28:31], v[188:191], v[156:159], v[28:31]
	v_mfma_f32_16x16x32_bf16 v[24:27], v[196:199], v[156:159], v[24:27]
	v_mfma_f32_16x16x32_bf16 v[20:23], v[188:191], v[164:167], v[20:23]
	v_mfma_f32_16x16x32_bf16 v[16:19], v[196:199], v[164:167], v[16:19]
	v_mfma_f32_16x16x32_bf16 v[12:15], v[188:191], v[172:175], v[12:15]
	v_mfma_f32_16x16x32_bf16 v[8:11], v[196:199], v[172:175], v[8:11]
	v_mfma_f32_16x16x32_bf16 v[4:7], v[188:191], v[180:183], v[4:7]
	v_mfma_f32_16x16x32_bf16 v[0:3], v[196:199], v[180:183], v[0:3]
	s_mov_b64 s[30:31], -1
	s_mov_b32 s8, 0
	s_branch .LBB0_318
